# v4 + QK/Q/K projection GEMM epilogue (EpiBf16 mode<3) rewritten by hand: branch-free inv_perm, hoisted ss loads, batched rstd
# baseline (speedup 1.0000x reference)
.LBB0_135:
	s_lshl_b32 s3, s46, 8
	v_readlane_b32 s1, v250, 38
	s_lshl_b32 s18, s2, 8
	s_add_i32 s3, s3, s1
	s_or_b32 s1, s18, s67
	v_or_b32_e32 v144, s3, v1
	s_andn2_b64 vcc, exec, s[12:13]
	v_or_b32_e32 v146, s1, v164
	s_cbranch_vccnz .LBB0_140
	s_and_b32 s19, s3, 0xfffff800
	s_lshl_b32 s100, s58, 1
	s_sub_i32 s101, 11, s100
	s_lshl_b32 s2, 1, s101
	s_add_i32 s2, s2, -1
	v_and_b32_e32 v149, 64, v220
	v_xor_b32_e32 v145, 16, v220
	v_add_u32_e32 v149, 64, v149
	v_cmp_lt_i32_e32 vcc, v145, v149
	v_xor_b32_e32 v150, 32, v220
	v_ashrrev_i32_e32 v147, 31, v146
	v_cndmask_b32_e32 v145, v220, v145, vcc
	v_cmp_lt_i32_e32 vcc, v150, v149
	v_lshlrev_b32_e32 v145, 2, v145
	v_lshl_add_u64 v[146:147], v[146:147], 1, s[74:75]
	v_cndmask_b32_e32 v150, v220, v150, vcc
	v_lshlrev_b32_e32 v150, 2, v150
	v_mov_b32_e32 v151, v144
	v_and_b32_e32 v209, 0x7ff, v151
	v_and_b32_e32 v151, s2, v209
	v_lshlrev_b32_e32 v151, s100, v151
	v_lshrrev_b32_e32 v209, s101, v209
	v_or3_b32 v151, v151, v209, s19
	v_lshlrev_b32_e32 v202, 7, v151
	v_mov_b32_e32 v203, 0
	v_lshl_add_u64 v[202:203], v[138:139], 0, v[202:203]
	v_add_u32_e32 v151, 0x10, v144
	v_and_b32_e32 v209, 0x7ff, v151
	v_and_b32_e32 v151, s2, v209
	v_lshlrev_b32_e32 v151, s100, v151
	v_lshrrev_b32_e32 v209, s101, v209
	v_or3_b32 v151, v151, v209, s19
	v_lshlrev_b32_e32 v204, 7, v151
	v_mov_b32_e32 v205, 0
	v_lshl_add_u64 v[204:205], v[138:139], 0, v[204:205]
	v_add_u32_e32 v151, 0x20, v144
	v_and_b32_e32 v209, 0x7ff, v151
	v_and_b32_e32 v151, s2, v209
	v_lshlrev_b32_e32 v151, s100, v151
	v_lshrrev_b32_e32 v209, s101, v209
	v_or3_b32 v151, v151, v209, s19
	v_lshlrev_b32_e32 v206, 7, v151
	v_mov_b32_e32 v207, 0
	v_lshl_add_u64 v[206:207], v[138:139], 0, v[206:207]
	v_add_u32_e32 v151, 0x30, v144
	v_and_b32_e32 v209, 0x7ff, v151
	v_and_b32_e32 v151, s2, v209
	v_lshlrev_b32_e32 v151, s100, v151
	v_lshrrev_b32_e32 v209, s101, v209
	v_or3_b32 v151, v151, v209, s19
	v_lshlrev_b32_e32 v208, 7, v151
	v_mov_b32_e32 v209, 0
	v_lshl_add_u64 v[208:209], v[138:139], 0, v[208:209]
	global_load_dwordx4 v[170:173], v[202:203], off
	global_load_dwordx4 v[174:177], v[202:203], off offset:16
	global_load_dwordx4 v[178:181], v[204:205], off
	global_load_dwordx4 v[182:185], v[204:205], off offset:16
	global_load_dwordx4 v[186:189], v[206:207], off
	global_load_dwordx4 v[190:193], v[206:207], off offset:16
	global_load_dwordx4 v[194:197], v[208:209], off
	global_load_dwordx4 v[198:201], v[208:209], off offset:16
	s_waitcnt vmcnt(0)
	v_add_f32_e32 v170, v170, v171
	v_add_f32_e32 v172, v172, v173
	v_add_f32_e32 v174, v174, v175
	v_add_f32_e32 v176, v176, v177
	v_add_f32_e32 v178, v178, v179
	v_add_f32_e32 v180, v180, v181
	v_add_f32_e32 v182, v182, v183
	v_add_f32_e32 v184, v184, v185
	v_add_f32_e32 v186, v186, v187
	v_add_f32_e32 v188, v188, v189
	v_add_f32_e32 v190, v190, v191
	v_add_f32_e32 v192, v192, v193
	v_add_f32_e32 v194, v194, v195
	v_add_f32_e32 v196, v196, v197
	v_add_f32_e32 v198, v198, v199
	v_add_f32_e32 v200, v200, v201
	v_add_f32_e32 v170, v170, v172
	v_add_f32_e32 v174, v174, v176
	v_add_f32_e32 v178, v178, v180
	v_add_f32_e32 v182, v182, v184
	v_add_f32_e32 v186, v186, v188
	v_add_f32_e32 v190, v190, v192
	v_add_f32_e32 v194, v194, v196
	v_add_f32_e32 v198, v198, v200
	v_add_f32_e32 v152, v170, v174
	v_add_f32_e32 v154, v178, v182
	v_add_f32_e32 v156, v186, v190
	v_add_f32_e32 v158, v194, v198
	v_add_u32_e32 v151, 0x80, v144
	v_and_b32_e32 v209, 0x7ff, v151
	v_and_b32_e32 v151, s2, v209
	v_lshlrev_b32_e32 v151, s100, v151
	v_lshrrev_b32_e32 v209, s101, v209
	v_or3_b32 v151, v151, v209, s19
	v_lshlrev_b32_e32 v202, 7, v151
	v_mov_b32_e32 v203, 0
	v_lshl_add_u64 v[202:203], v[138:139], 0, v[202:203]
	v_add_u32_e32 v151, 0x90, v144
	v_and_b32_e32 v209, 0x7ff, v151
	v_and_b32_e32 v151, s2, v209
	v_lshlrev_b32_e32 v151, s100, v151
	v_lshrrev_b32_e32 v209, s101, v209
	v_or3_b32 v151, v151, v209, s19
	v_lshlrev_b32_e32 v204, 7, v151
	v_mov_b32_e32 v205, 0
	v_lshl_add_u64 v[204:205], v[138:139], 0, v[204:205]
	v_add_u32_e32 v151, 0xa0, v144
	v_and_b32_e32 v209, 0x7ff, v151
	v_and_b32_e32 v151, s2, v209
	v_lshlrev_b32_e32 v151, s100, v151
	v_lshrrev_b32_e32 v209, s101, v209
	v_or3_b32 v151, v151, v209, s19
	v_lshlrev_b32_e32 v206, 7, v151
	v_mov_b32_e32 v207, 0
	v_lshl_add_u64 v[206:207], v[138:139], 0, v[206:207]
	v_add_u32_e32 v151, 0xb0, v144
	v_and_b32_e32 v209, 0x7ff, v151
	v_and_b32_e32 v151, s2, v209
	v_lshlrev_b32_e32 v151, s100, v151
	v_lshrrev_b32_e32 v209, s101, v209
	v_or3_b32 v151, v151, v209, s19
	v_lshlrev_b32_e32 v208, 7, v151
	v_mov_b32_e32 v209, 0
	v_lshl_add_u64 v[208:209], v[138:139], 0, v[208:209]
	global_load_dwordx4 v[170:173], v[202:203], off
	global_load_dwordx4 v[174:177], v[202:203], off offset:16
	global_load_dwordx4 v[178:181], v[204:205], off
	global_load_dwordx4 v[182:185], v[204:205], off offset:16
	global_load_dwordx4 v[186:189], v[206:207], off
	global_load_dwordx4 v[190:193], v[206:207], off offset:16
	global_load_dwordx4 v[194:197], v[208:209], off
	global_load_dwordx4 v[198:201], v[208:209], off offset:16
	ds_bpermute_b32 v153, v145, v152
	ds_bpermute_b32 v155, v145, v154
	ds_bpermute_b32 v157, v145, v156
	ds_bpermute_b32 v159, v145, v158
	s_waitcnt lgkmcnt(0)
	v_add_f32_e32 v152, v152, v153
	v_add_f32_e32 v154, v154, v155
	v_add_f32_e32 v156, v156, v157
	v_add_f32_e32 v158, v158, v159
	ds_bpermute_b32 v153, v150, v152
	ds_bpermute_b32 v155, v150, v154
	ds_bpermute_b32 v157, v150, v156
	ds_bpermute_b32 v159, v150, v158
	s_waitcnt lgkmcnt(0)
	v_add_f32_e32 v152, v152, v153
	v_add_f32_e32 v154, v154, v155
	v_add_f32_e32 v156, v156, v157
	v_add_f32_e32 v158, v158, v159
	v_fmamk_f32 v152, v152, 0x3a000000, v216
	v_cmp_gt_f32_e32 vcc, s65, v152
	v_mul_f32_e32 v153, 0x4b800000, v152
	s_nop 0
	v_cndmask_b32_e32 v152, v152, v153, vcc
	v_rsq_f32_e32 v152, v152
	s_nop 0
	v_mul_f32_e32 v153, 0x45800000, v152
	v_cndmask_b32_e32 v152, v152, v153, vcc
	v_fmamk_f32 v154, v154, 0x3a000000, v216
	v_cmp_gt_f32_e32 vcc, s65, v154
	v_mul_f32_e32 v155, 0x4b800000, v154
	s_nop 0
	v_cndmask_b32_e32 v154, v154, v155, vcc
	v_rsq_f32_e32 v154, v154
	s_nop 0
	v_mul_f32_e32 v155, 0x45800000, v154
	v_cndmask_b32_e32 v154, v154, v155, vcc
	v_fmamk_f32 v156, v156, 0x3a000000, v216
	v_cmp_gt_f32_e32 vcc, s65, v156
	v_mul_f32_e32 v157, 0x4b800000, v156
	s_nop 0
	v_cndmask_b32_e32 v156, v156, v157, vcc
	v_rsq_f32_e32 v156, v156
	s_nop 0
	v_mul_f32_e32 v157, 0x45800000, v156
	v_cndmask_b32_e32 v156, v156, v157, vcc
	v_fmamk_f32 v158, v158, 0x3a000000, v216
	v_cmp_gt_f32_e32 vcc, s65, v158
	v_mul_f32_e32 v159, 0x4b800000, v158
	s_nop 0
	v_cndmask_b32_e32 v158, v158, v159, vcc
	v_rsq_f32_e32 v158, v158
	s_nop 0
	v_mul_f32_e32 v159, 0x45800000, v158
	v_cndmask_b32_e32 v158, v158, v159, vcc
	v_mov_b32_e32 v151, v144
	v_mad_i64_i32 v[148:149], vcc, v151, s78, 0
	v_pk_mul_f32 v[210:211], v[126:127], v[152:153] op_sel_hi:[1,0]
	v_pk_mul_f32 v[212:213], v[128:129], v[152:153] op_sel_hi:[1,0]
	v_pk_mul_f32 v[160:161], v[122:123], v[152:153] op_sel_hi:[1,0]
	v_pk_mul_f32 v[162:163], v[124:125], v[152:153] op_sel_hi:[1,0]
	v_lshl_add_u64 v[148:149], v[148:149], 1, v[146:147]
	v_cvt_pk_bf16_f32 v206, v210, v211
	v_cvt_pk_bf16_f32 v207, v212, v213
	v_cvt_pk_bf16_f32 v208, v160, v161
	v_cvt_pk_bf16_f32 v209, v162, v163
	global_store_dwordx4 v[148:149], v[206:209], off
	v_pk_mul_f32 v[210:211], v[118:119], v[152:153] op_sel_hi:[1,0]
	v_pk_mul_f32 v[212:213], v[120:121], v[152:153] op_sel_hi:[1,0]
	v_pk_mul_f32 v[160:161], v[114:115], v[152:153] op_sel_hi:[1,0]
	v_pk_mul_f32 v[162:163], v[116:117], v[152:153] op_sel_hi:[1,0]
	v_cvt_pk_bf16_f32 v206, v210, v211
	v_cvt_pk_bf16_f32 v207, v212, v213
	v_cvt_pk_bf16_f32 v208, v160, v161
	v_cvt_pk_bf16_f32 v209, v162, v163
	global_store_dwordx4 v[148:149], v[206:209], off offset:256
	v_add_u32_e32 v151, 0x10, v144
	v_mad_i64_i32 v[148:149], vcc, v151, s78, 0
	v_pk_mul_f32 v[210:211], v[110:111], v[154:155] op_sel_hi:[1,0]
	v_pk_mul_f32 v[212:213], v[112:113], v[154:155] op_sel_hi:[1,0]
	v_pk_mul_f32 v[160:161], v[106:107], v[154:155] op_sel_hi:[1,0]
	v_pk_mul_f32 v[162:163], v[108:109], v[154:155] op_sel_hi:[1,0]
	v_lshl_add_u64 v[148:149], v[148:149], 1, v[146:147]
	v_cvt_pk_bf16_f32 v206, v210, v211
	v_cvt_pk_bf16_f32 v207, v212, v213
	v_cvt_pk_bf16_f32 v208, v160, v161
	v_cvt_pk_bf16_f32 v209, v162, v163
	global_store_dwordx4 v[148:149], v[206:209], off
	v_pk_mul_f32 v[210:211], v[98:99], v[154:155] op_sel_hi:[1,0]
	v_pk_mul_f32 v[212:213], v[100:101], v[154:155] op_sel_hi:[1,0]
	v_pk_mul_f32 v[160:161], v[90:91], v[154:155] op_sel_hi:[1,0]
	v_pk_mul_f32 v[162:163], v[92:93], v[154:155] op_sel_hi:[1,0]
	v_cvt_pk_bf16_f32 v206, v210, v211
	v_cvt_pk_bf16_f32 v207, v212, v213
	v_cvt_pk_bf16_f32 v208, v160, v161
	v_cvt_pk_bf16_f32 v209, v162, v163
	global_store_dwordx4 v[148:149], v[206:209], off offset:256
	v_add_u32_e32 v151, 0x20, v144
	v_mad_i64_i32 v[148:149], vcc, v151, s78, 0
	v_pk_mul_f32 v[210:211], v[102:103], v[156:157] op_sel_hi:[1,0]
	v_pk_mul_f32 v[212:213], v[104:105], v[156:157] op_sel_hi:[1,0]
	v_pk_mul_f32 v[160:161], v[94:95], v[156:157] op_sel_hi:[1,0]
	v_pk_mul_f32 v[162:163], v[96:97], v[156:157] op_sel_hi:[1,0]
	v_lshl_add_u64 v[148:149], v[148:149], 1, v[146:147]
	v_cvt_pk_bf16_f32 v206, v210, v211
	v_cvt_pk_bf16_f32 v207, v212, v213
	v_cvt_pk_bf16_f32 v208, v160, v161
	v_cvt_pk_bf16_f32 v209, v162, v163
	global_store_dwordx4 v[148:149], v[206:209], off
	v_pk_mul_f32 v[210:211], v[82:83], v[156:157] op_sel_hi:[1,0]
	v_pk_mul_f32 v[212:213], v[84:85], v[156:157] op_sel_hi:[1,0]
	v_pk_mul_f32 v[160:161], v[74:75], v[156:157] op_sel_hi:[1,0]
	v_pk_mul_f32 v[162:163], v[76:77], v[156:157] op_sel_hi:[1,0]
	v_cvt_pk_bf16_f32 v206, v210, v211
	v_cvt_pk_bf16_f32 v207, v212, v213
	v_cvt_pk_bf16_f32 v208, v160, v161
	v_cvt_pk_bf16_f32 v209, v162, v163
	global_store_dwordx4 v[148:149], v[206:209], off offset:256
	v_add_u32_e32 v151, 0x30, v144
	v_mad_i64_i32 v[148:149], vcc, v151, s78, 0
	v_pk_mul_f32 v[210:211], v[86:87], v[158:159] op_sel_hi:[1,0]
	v_pk_mul_f32 v[212:213], v[88:89], v[158:159] op_sel_hi:[1,0]
	v_pk_mul_f32 v[160:161], v[78:79], v[158:159] op_sel_hi:[1,0]
	v_pk_mul_f32 v[162:163], v[80:81], v[158:159] op_sel_hi:[1,0]
	v_lshl_add_u64 v[148:149], v[148:149], 1, v[146:147]
	v_cvt_pk_bf16_f32 v206, v210, v211
	v_cvt_pk_bf16_f32 v207, v212, v213
	v_cvt_pk_bf16_f32 v208, v160, v161
	v_cvt_pk_bf16_f32 v209, v162, v163
	global_store_dwordx4 v[148:149], v[206:209], off
	v_pk_mul_f32 v[210:211], v[70:71], v[158:159] op_sel_hi:[1,0]
	v_pk_mul_f32 v[212:213], v[72:73], v[158:159] op_sel_hi:[1,0]
	v_pk_mul_f32 v[160:161], v[66:67], v[158:159] op_sel_hi:[1,0]
	v_pk_mul_f32 v[162:163], v[68:69], v[158:159] op_sel_hi:[1,0]
	v_cvt_pk_bf16_f32 v206, v210, v211
	v_cvt_pk_bf16_f32 v207, v212, v213
	v_cvt_pk_bf16_f32 v208, v160, v161
	v_cvt_pk_bf16_f32 v209, v162, v163
	global_store_dwordx4 v[148:149], v[206:209], off offset:256
	s_waitcnt vmcnt(8)
	v_add_f32_e32 v170, v170, v171
	v_add_f32_e32 v172, v172, v173
	v_add_f32_e32 v174, v174, v175
	v_add_f32_e32 v176, v176, v177
	v_add_f32_e32 v178, v178, v179
	v_add_f32_e32 v180, v180, v181
	v_add_f32_e32 v182, v182, v183
	v_add_f32_e32 v184, v184, v185
	v_add_f32_e32 v186, v186, v187
	v_add_f32_e32 v188, v188, v189
	v_add_f32_e32 v190, v190, v191
	v_add_f32_e32 v192, v192, v193
	v_add_f32_e32 v194, v194, v195
	v_add_f32_e32 v196, v196, v197
	v_add_f32_e32 v198, v198, v199
	v_add_f32_e32 v200, v200, v201
	v_add_f32_e32 v170, v170, v172
	v_add_f32_e32 v174, v174, v176
	v_add_f32_e32 v178, v178, v180
	v_add_f32_e32 v182, v182, v184
	v_add_f32_e32 v186, v186, v188
	v_add_f32_e32 v190, v190, v192
	v_add_f32_e32 v194, v194, v196
	v_add_f32_e32 v198, v198, v200
	v_add_f32_e32 v152, v170, v174
	v_add_f32_e32 v154, v178, v182
	v_add_f32_e32 v156, v186, v190
	v_add_f32_e32 v158, v194, v198
	ds_bpermute_b32 v153, v145, v152
	ds_bpermute_b32 v155, v145, v154
	ds_bpermute_b32 v157, v145, v156
	ds_bpermute_b32 v159, v145, v158
	s_waitcnt lgkmcnt(0)
	v_add_f32_e32 v152, v152, v153
	v_add_f32_e32 v154, v154, v155
	v_add_f32_e32 v156, v156, v157
	v_add_f32_e32 v158, v158, v159
	ds_bpermute_b32 v153, v150, v152
	ds_bpermute_b32 v155, v150, v154
	ds_bpermute_b32 v157, v150, v156
	ds_bpermute_b32 v159, v150, v158
	s_waitcnt lgkmcnt(0)
	v_add_f32_e32 v152, v152, v153
	v_add_f32_e32 v154, v154, v155
	v_add_f32_e32 v156, v156, v157
	v_add_f32_e32 v158, v158, v159
	v_fmamk_f32 v152, v152, 0x3a000000, v216
	v_cmp_gt_f32_e32 vcc, s65, v152
	v_mul_f32_e32 v153, 0x4b800000, v152
	s_nop 0
	v_cndmask_b32_e32 v152, v152, v153, vcc
	v_rsq_f32_e32 v152, v152
	s_nop 0
	v_mul_f32_e32 v153, 0x45800000, v152
	v_cndmask_b32_e32 v152, v152, v153, vcc
	v_fmamk_f32 v154, v154, 0x3a000000, v216
	v_cmp_gt_f32_e32 vcc, s65, v154
	v_mul_f32_e32 v155, 0x4b800000, v154
	s_nop 0
	v_cndmask_b32_e32 v154, v154, v155, vcc
	v_rsq_f32_e32 v154, v154
	s_nop 0
	v_mul_f32_e32 v155, 0x45800000, v154
	v_cndmask_b32_e32 v154, v154, v155, vcc
	v_fmamk_f32 v156, v156, 0x3a000000, v216
	v_cmp_gt_f32_e32 vcc, s65, v156
	v_mul_f32_e32 v157, 0x4b800000, v156
	s_nop 0
	v_cndmask_b32_e32 v156, v156, v157, vcc
	v_rsq_f32_e32 v156, v156
	s_nop 0
	v_mul_f32_e32 v157, 0x45800000, v156
	v_cndmask_b32_e32 v156, v156, v157, vcc
	v_fmamk_f32 v158, v158, 0x3a000000, v216
	v_cmp_gt_f32_e32 vcc, s65, v158
	v_mul_f32_e32 v159, 0x4b800000, v158
	s_nop 0
	v_cndmask_b32_e32 v158, v158, v159, vcc
	v_rsq_f32_e32 v158, v158
	s_nop 0
	v_mul_f32_e32 v159, 0x45800000, v158
	v_cndmask_b32_e32 v158, v158, v159, vcc
	v_add_u32_e32 v151, 0x80, v144
	v_mad_i64_i32 v[148:149], vcc, v151, s78, 0
	v_pk_mul_f32 v[210:211], v[62:63], v[152:153] op_sel_hi:[1,0]
	v_pk_mul_f32 v[212:213], v[64:65], v[152:153] op_sel_hi:[1,0]
	v_pk_mul_f32 v[160:161], v[58:59], v[152:153] op_sel_hi:[1,0]
	v_pk_mul_f32 v[162:163], v[60:61], v[152:153] op_sel_hi:[1,0]
	v_lshl_add_u64 v[148:149], v[148:149], 1, v[146:147]
	v_cvt_pk_bf16_f32 v206, v210, v211
	v_cvt_pk_bf16_f32 v207, v212, v213
	v_cvt_pk_bf16_f32 v208, v160, v161
	v_cvt_pk_bf16_f32 v209, v162, v163
	global_store_dwordx4 v[148:149], v[206:209], off
	v_pk_mul_f32 v[210:211], v[50:51], v[152:153] op_sel_hi:[1,0]
	v_pk_mul_f32 v[212:213], v[52:53], v[152:153] op_sel_hi:[1,0]
	v_pk_mul_f32 v[160:161], v[42:43], v[152:153] op_sel_hi:[1,0]
	v_pk_mul_f32 v[162:163], v[44:45], v[152:153] op_sel_hi:[1,0]
	v_cvt_pk_bf16_f32 v206, v210, v211
	v_cvt_pk_bf16_f32 v207, v212, v213
	v_cvt_pk_bf16_f32 v208, v160, v161
	v_cvt_pk_bf16_f32 v209, v162, v163
	global_store_dwordx4 v[148:149], v[206:209], off offset:256
	v_add_u32_e32 v151, 0x90, v144
	v_mad_i64_i32 v[148:149], vcc, v151, s78, 0
	v_pk_mul_f32 v[210:211], v[54:55], v[154:155] op_sel_hi:[1,0]
	v_pk_mul_f32 v[212:213], v[56:57], v[154:155] op_sel_hi:[1,0]
	v_pk_mul_f32 v[160:161], v[46:47], v[154:155] op_sel_hi:[1,0]
	v_pk_mul_f32 v[162:163], v[48:49], v[154:155] op_sel_hi:[1,0]
	v_lshl_add_u64 v[148:149], v[148:149], 1, v[146:147]
	v_cvt_pk_bf16_f32 v206, v210, v211
	v_cvt_pk_bf16_f32 v207, v212, v213
	v_cvt_pk_bf16_f32 v208, v160, v161
	v_cvt_pk_bf16_f32 v209, v162, v163
	global_store_dwordx4 v[148:149], v[206:209], off
	v_pk_mul_f32 v[210:211], v[34:35], v[154:155] op_sel_hi:[1,0]
	v_pk_mul_f32 v[212:213], v[36:37], v[154:155] op_sel_hi:[1,0]
	v_pk_mul_f32 v[160:161], v[26:27], v[154:155] op_sel_hi:[1,0]
	v_pk_mul_f32 v[162:163], v[28:29], v[154:155] op_sel_hi:[1,0]
	v_cvt_pk_bf16_f32 v206, v210, v211
	v_cvt_pk_bf16_f32 v207, v212, v213
	v_cvt_pk_bf16_f32 v208, v160, v161
	v_cvt_pk_bf16_f32 v209, v162, v163
	global_store_dwordx4 v[148:149], v[206:209], off offset:256
	v_add_u32_e32 v151, 0xa0, v144
	v_mad_i64_i32 v[148:149], vcc, v151, s78, 0
	v_pk_mul_f32 v[210:211], v[38:39], v[156:157] op_sel_hi:[1,0]
	v_pk_mul_f32 v[212:213], v[40:41], v[156:157] op_sel_hi:[1,0]
	v_pk_mul_f32 v[160:161], v[30:31], v[156:157] op_sel_hi:[1,0]
	v_pk_mul_f32 v[162:163], v[32:33], v[156:157] op_sel_hi:[1,0]
	v_lshl_add_u64 v[148:149], v[148:149], 1, v[146:147]
	v_cvt_pk_bf16_f32 v206, v210, v211
	v_cvt_pk_bf16_f32 v207, v212, v213
	v_cvt_pk_bf16_f32 v208, v160, v161
	v_cvt_pk_bf16_f32 v209, v162, v163
	global_store_dwordx4 v[148:149], v[206:209], off
	v_pk_mul_f32 v[210:211], v[18:19], v[156:157] op_sel_hi:[1,0]
	v_pk_mul_f32 v[212:213], v[20:21], v[156:157] op_sel_hi:[1,0]
	v_pk_mul_f32 v[160:161], v[10:11], v[156:157] op_sel_hi:[1,0]
	v_pk_mul_f32 v[162:163], v[12:13], v[156:157] op_sel_hi:[1,0]
	v_cvt_pk_bf16_f32 v206, v210, v211
	v_cvt_pk_bf16_f32 v207, v212, v213
	v_cvt_pk_bf16_f32 v208, v160, v161
	v_cvt_pk_bf16_f32 v209, v162, v163
	global_store_dwordx4 v[148:149], v[206:209], off offset:256
	v_add_u32_e32 v151, 0xb0, v144
	v_mad_i64_i32 v[148:149], vcc, v151, s78, 0
	v_pk_mul_f32 v[210:211], v[22:23], v[158:159] op_sel_hi:[1,0]
	v_pk_mul_f32 v[212:213], v[24:25], v[158:159] op_sel_hi:[1,0]
	v_pk_mul_f32 v[160:161], v[14:15], v[158:159] op_sel_hi:[1,0]
	v_pk_mul_f32 v[162:163], v[16:17], v[158:159] op_sel_hi:[1,0]
	v_lshl_add_u64 v[148:149], v[148:149], 1, v[146:147]
	v_cvt_pk_bf16_f32 v206, v210, v211
	v_cvt_pk_bf16_f32 v207, v212, v213
	v_cvt_pk_bf16_f32 v208, v160, v161
	v_cvt_pk_bf16_f32 v209, v162, v163
	global_store_dwordx4 v[148:149], v[206:209], off
	v_pk_mul_f32 v[210:211], v[6:7], v[158:159] op_sel_hi:[1,0]
	v_pk_mul_f32 v[212:213], v[8:9], v[158:159] op_sel_hi:[1,0]
	v_pk_mul_f32 v[160:161], v[2:3], v[158:159] op_sel_hi:[1,0]
	v_pk_mul_f32 v[162:163], v[4:5], v[158:159] op_sel_hi:[1,0]
	v_cvt_pk_bf16_f32 v206, v210, v211
	v_cvt_pk_bf16_f32 v207, v212, v213
	v_cvt_pk_bf16_f32 v208, v160, v161
	v_cvt_pk_bf16_f32 v209, v162, v163
	global_store_dwordx4 v[148:149], v[206:209], off offset:256
	s_branch .LBB0_211
.LBB0_140:
	s_cbranch_execnz .LBB0_202
	s_branch .LBB0_211
.LBB0_202:
	s_and_b32 s18, s18, 0xfffff800
	v_or_b32_e32 v145, v166, v146
	s_cmp_lt_i32 s58, 4
	v_bitop3_b32 v147, v166, s27, v146 bitop3:0xc8
	s_cbranch_scc1 .LBB0_206
	s_cmp_eq_u32 s58, 4
	s_mov_b64 s[2:3], -1
	s_cbranch_scc0 .LBB0_205
	v_lshlrev_b32_e32 v148, 2, v145
	v_and_b32_e32 v148, 0x7fc, v148
	v_lshrrev_b32_e32 v149, 9, v147
	v_or3_b32 v148, v148, v149, s18
	s_mov_b64 s[2:3], 0

	.amdhsa_kernel _Z3fwd4Args
		.amdhsa_group_segment_fixed_size 0
		.amdhsa_private_segment_fixed_size 0
		.amdhsa_kernarg_size 384
		.amdhsa_user_sgpr_count 2
		.amdhsa_user_sgpr_dispatch_ptr 0
		.amdhsa_user_sgpr_queue_ptr 0
		.amdhsa_user_sgpr_kernarg_segment_ptr 1
		.amdhsa_user_sgpr_dispatch_id 0
		.amdhsa_user_sgpr_kernarg_preload_length 0
		.amdhsa_user_sgpr_kernarg_preload_offset 0
		.amdhsa_user_sgpr_private_segment_size 0
		.amdhsa_uses_dynamic_stack 0
		.amdhsa_enable_private_segment 0
		.amdhsa_system_sgpr_workgroup_id_x 1
		.amdhsa_system_sgpr_workgroup_id_y 0
		.amdhsa_system_sgpr_workgroup_id_z 0
		.amdhsa_system_sgpr_workgroup_info 0
		.amdhsa_system_vgpr_workitem_id 2
		.amdhsa_next_free_vgpr 253
		.amdhsa_next_free_sgpr 102
		.amdhsa_accum_offset 256
		.amdhsa_reserve_vcc 1
		.amdhsa_float_round_mode_32 0
		.amdhsa_float_round_mode_16_64 0
		.amdhsa_float_denorm_mode_32 3
		.amdhsa_float_denorm_mode_16_64 3
		.amdhsa_dx10_clamp 1
		.amdhsa_ieee_mode 1
		.amdhsa_fp16_overflow 0
		.amdhsa_tg_split 0
		.amdhsa_exception_fp_ieee_invalid_op 0
		.amdhsa_exception_fp_denorm_src 0
		.amdhsa_exception_fp_ieee_div_zero 0
		.amdhsa_exception_fp_ieee_overflow 0
		.amdhsa_exception_fp_ieee_underflow 0
		.amdhsa_exception_fp_ieee_inexact 0
		.amdhsa_exception_int_div_zero 0
	.end_amdhsa_kernel

amdhsa.kernels:
  - .agpr_count:     0
    .args:
      - .offset:         0
        .size:           128
        .value_kind:     by_value
      - .offset:         128
        .size:           4
        .value_kind:     hidden_block_count_x
      - .offset:         132
        .size:           4
        .value_kind:     hidden_block_count_y
      - .offset:         136
        .size:           4
        .value_kind:     hidden_block_count_z
      - .offset:         140
        .size:           2
        .value_kind:     hidden_group_size_x
      - .offset:         142
        .size:           2
        .value_kind:     hidden_group_size_y
      - .offset:         144
        .size:           2
        .value_kind:     hidden_group_size_z
      - .offset:         146
        .size:           2
        .value_kind:     hidden_remainder_x
      - .offset:         148
        .size:           2
        .value_kind:     hidden_remainder_y
      - .offset:         150
        .size:           2
        .value_kind:     hidden_remainder_z
      - .offset:         168
        .size:           8
        .value_kind:     hidden_global_offset_x
      - .offset:         176
        .size:           8
        .value_kind:     hidden_global_offset_y
      - .offset:         184
        .size:           8
        .value_kind:     hidden_global_offset_z
      - .offset:         192
        .size:           2
        .value_kind:     hidden_grid_dims
      - .offset:         216
        .size:           8
        .value_kind:     hidden_multigrid_sync_arg
      - .offset:         248
        .size:           4
        .value_kind:     hidden_dynamic_lds_size
    .group_segment_fixed_size: 0
    .kernarg_segment_align: 8
    .kernarg_segment_size: 384
    .language:       OpenCL C
    .language_version:
      - 2
      - 0
    .max_flat_workgroup_size: 512
    .name:           _Z3fwd4Args
    .private_segment_fixed_size: 0
    .sgpr_count:     108
    .sgpr_spill_count: 189
    .symbol:         _Z3fwd4Args.kd
    .uniform_work_group_size: 1
    .uses_dynamic_stack: false
    .vgpr_count:     253
    .vgpr_spill_count: 0
    .wavefront_size: 64
